# GEMM accumulator zeroing with 64-bit moves (halves the per-tile zeroing instruction count)
# speedup vs baseline: 1.0400x; 1.0054x over previous
; template <class Epi>
; DI void gemm_phase(int wv, LAS unsigned char* lds, const Gemm g, const StaticOrder& S, const Epi& E) {
;     ...
;     const bool has_next = S.next(ui + 1, nxt);
;     const char* nA = has_next ? (const char*)g.A + (size_t)nxt.pm * tstep : cA; const char* nB = has_next ? (const char*)g.Bt + (size_t)nxt.pn * tstep : cB;
;     for (int t = 0; t < nt; t += 2) {
;       const bool last = (t == nt - 2);
;       const char* a1 = cA + (size_t)(t + 1) * kstep;
;       const char* a2 = last ? nA : cA + (size_t)(t + 2) * kstep; const char* b2 = last ? nB : cB + (size_t)(t + 2) * kstep;
;     ...
; #pragma unroll
;     for (int a = 0; a < 2; ++a)
; #pragma unroll
;       for (int b = 0; b < 2; ++b)
; #pragma unroll
;         for (int m = 0; m < 4; ++m)
; #pragma unroll
;           for (int n = 0; n < 2; ++n) acc[a][b][m][n] = (f32x4){0.f, 0.f, 0.f, 0.f};
.LBB0_208:
	s_ashr_i32 s15, s14, 31
	s_lshl_b64 s[16:17], s[14:15], 19
	s_add_u32 s16, s76, s16
	v_cmp_lt_i64_e64 s[6:7], s[6:7], v[196:197]
	s_addc_u32 s17, s77, s17
	s_and_b64 s[18:19], s[6:7], exec
	s_cselect_b32 s15, s17, s21
	s_cselect_b32 s54, s16, s20
	s_ashr_i32 s13, s12, 31
	s_lshl_b64 s[18:19], s[12:13], 19
	s_add_u32 s18, s31, s18
	s_addc_u32 s19, s33, s19
	s_and_b64 s[24:25], s[6:7], exec
	s_cselect_b32 s13, s19, s23
	s_cselect_b32 s57, s18, s22
	s_add_u32 s20, s20, 0x40080
	s_addc_u32 s21, s21, 0
	s_add_u32 s60, s22, 0x100
	v_mov_b32_e32 v0, 0
	s_addc_u32 s61, s23, 0
	s_mov_b32 s62, -2
	v_mov_b32_e32 v1, v0
	v_mov_b64_e32 v[2:3], v[0:1]
	v_mov_b64_e32 v[4:5], v[0:1]
	v_mov_b64_e32 v[6:7], v[0:1]
	v_mov_b64_e32 v[8:9], v[0:1]
	v_mov_b64_e32 v[10:11], v[0:1]
	v_mov_b64_e32 v[12:13], v[0:1]
	v_mov_b64_e32 v[14:15], v[0:1]
	v_mov_b64_e32 v[16:17], v[0:1]
	v_mov_b64_e32 v[18:19], v[0:1]
	v_mov_b64_e32 v[20:21], v[0:1]
	v_mov_b64_e32 v[22:23], v[0:1]
	v_mov_b64_e32 v[24:25], v[0:1]
	v_mov_b64_e32 v[26:27], v[0:1]
	v_mov_b64_e32 v[28:29], v[0:1]
	v_mov_b64_e32 v[30:31], v[0:1]
	v_mov_b64_e32 v[34:35], v[0:1]
	v_mov_b64_e32 v[36:37], v[0:1]
	v_mov_b64_e32 v[38:39], v[0:1]
	v_mov_b64_e32 v[40:41], v[0:1]
	v_mov_b64_e32 v[42:43], v[0:1]
	v_mov_b64_e32 v[44:45], v[0:1]
	v_mov_b64_e32 v[46:47], v[0:1]
	v_mov_b64_e32 v[48:49], v[0:1]
	v_mov_b64_e32 v[50:51], v[0:1]
	v_mov_b64_e32 v[52:53], v[0:1]
	v_mov_b64_e32 v[54:55], v[0:1]
	v_mov_b64_e32 v[56:57], v[0:1]
	v_mov_b64_e32 v[58:59], v[0:1]
	v_mov_b64_e32 v[60:61], v[0:1]
	v_mov_b64_e32 v[62:63], v[0:1]
	v_mov_b64_e32 v[64:65], v[0:1]
	v_mov_b64_e32 v[66:67], v[0:1]
	v_mov_b64_e32 v[68:69], v[0:1]
	v_mov_b64_e32 v[70:71], v[0:1]
	v_mov_b64_e32 v[72:73], v[0:1]
	v_mov_b64_e32 v[74:75], v[0:1]
	v_mov_b64_e32 v[76:77], v[0:1]
	v_mov_b64_e32 v[78:79], v[0:1]
	v_mov_b64_e32 v[80:81], v[0:1]
	v_mov_b64_e32 v[82:83], v[0:1]
	v_mov_b64_e32 v[84:85], v[0:1]
	v_mov_b64_e32 v[86:87], v[0:1]
	v_mov_b64_e32 v[88:89], v[0:1]
	v_mov_b64_e32 v[90:91], v[0:1]
	v_mov_b64_e32 v[92:93], v[0:1]
	v_mov_b64_e32 v[94:95], v[0:1]
	v_mov_b64_e32 v[96:97], v[0:1]
	s_waitcnt vmcnt(0)
	v_mov_b64_e32 v[98:99], v[0:1]
	v_mov_b64_e32 v[100:101], v[0:1]
	v_mov_b64_e32 v[102:103], v[0:1]
	v_mov_b64_e32 v[104:105], v[0:1]
	v_mov_b64_e32 v[106:107], v[0:1]
	v_mov_b64_e32 v[108:109], v[0:1]
	v_mov_b64_e32 v[110:111], v[0:1]
	v_mov_b64_e32 v[112:113], v[0:1]
	v_mov_b64_e32 v[114:115], v[0:1]
	v_mov_b64_e32 v[116:117], v[0:1]
	v_mov_b64_e32 v[118:119], v[0:1]
	v_mov_b64_e32 v[120:121], v[0:1]
	v_mov_b64_e32 v[122:123], v[0:1]
	v_mov_b64_e32 v[124:125], v[0:1]
	v_mov_b64_e32 v[126:127], v[0:1]
	v_mov_b64_e32 v[128:129], v[0:1]

; template <class Epi>
; DI void gemm_phase(int wv, LAS unsigned char* lds, const Gemm g, const StaticOrder& S, const Epi& E) {
;     ...
;     const bool has_next = S.next(ui + 1, nxt);
;     const char* nA = has_next ? (const char*)g.A + (size_t)nxt.pm * tstep : cA; const char* nB = has_next ? (const char*)g.Bt + (size_t)nxt.pn * tstep : cB;
;     for (int t = 0; t < nt; t += 2) {
;       const bool last = (t == nt - 2);
;       const char* a1 = cA + (size_t)(t + 1) * kstep;
;       const char* a2 = last ? nA : cA + (size_t)(t + 2) * kstep; const char* b2 = last ? nB : cB + (size_t)(t + 2) * kstep;
;     ...
; #pragma unroll
;     for (int a = 0; a < 2; ++a)
; #pragma unroll
;       for (int b = 0; b < 2; ++b)
; #pragma unroll
;         for (int m = 0; m < 4; ++m)
; #pragma unroll
;           for (int n = 0; n < 2; ++n) acc[a][b][m][n] = (f32x4){0.f, 0.f, 0.f, 0.f};
.LBB0_292:
	s_ashr_i32 s21, s20, 31
	s_lshl_b64 s[22:23], s[20:21], 19
	s_add_u32 s22, s76, s22
	s_addc_u32 s23, s77, s23
	s_and_b64 s[24:25], s[6:7], exec
	s_cselect_b32 s21, s23, s31
	s_cselect_b32 s29, s22, s30
	s_ashr_i32 s19, s18, 31
	s_lshl_b64 s[24:25], s[18:19], 19
	s_add_u32 s24, s82, s24
	s_addc_u32 s25, s83, s25
	s_and_b64 s[36:37], s[6:7], exec
	s_cselect_b32 s19, s25, s35
	s_cselect_b32 s33, s24, s34
	s_add_u32 s30, s30, 0x40080
	s_addc_u32 s31, s31, 0
	s_add_u32 s49, s34, 0x100
	v_mov_b32_e32 v0, 0
	s_addc_u32 s50, s35, 0
	s_mov_b32 s51, -2
	v_mov_b32_e32 v1, v0
	v_mov_b64_e32 v[2:3], v[0:1]
	v_mov_b64_e32 v[4:5], v[0:1]
	v_mov_b64_e32 v[6:7], v[0:1]
	v_mov_b64_e32 v[16:17], v[0:1]
	v_mov_b64_e32 v[18:19], v[0:1]
	v_mov_b64_e32 v[20:21], v[0:1]
	v_mov_b64_e32 v[22:23], v[0:1]
	v_mov_b64_e32 v[34:35], v[0:1]
	v_mov_b64_e32 v[36:37], v[0:1]
	v_mov_b64_e32 v[38:39], v[0:1]
	v_mov_b64_e32 v[40:41], v[0:1]
	v_mov_b64_e32 v[50:51], v[0:1]
	v_mov_b64_e32 v[52:53], v[0:1]
	v_mov_b64_e32 v[54:55], v[0:1]
	v_mov_b64_e32 v[56:57], v[0:1]
	v_mov_b64_e32 v[8:9], v[0:1]
	v_mov_b64_e32 v[10:11], v[0:1]
	v_mov_b64_e32 v[12:13], v[0:1]
	v_mov_b64_e32 v[14:15], v[0:1]
	v_mov_b64_e32 v[24:25], v[0:1]
	v_mov_b64_e32 v[26:27], v[0:1]
	v_mov_b64_e32 v[28:29], v[0:1]
	v_mov_b64_e32 v[30:31], v[0:1]
	v_mov_b64_e32 v[42:43], v[0:1]
	v_mov_b64_e32 v[44:45], v[0:1]
	v_mov_b64_e32 v[46:47], v[0:1]
	v_mov_b64_e32 v[48:49], v[0:1]
	v_mov_b64_e32 v[58:59], v[0:1]
	v_mov_b64_e32 v[60:61], v[0:1]
	v_mov_b64_e32 v[62:63], v[0:1]
	v_mov_b64_e32 v[64:65], v[0:1]
	v_mov_b64_e32 v[66:67], v[0:1]
	v_mov_b64_e32 v[68:69], v[0:1]
	v_mov_b64_e32 v[70:71], v[0:1]
	v_mov_b64_e32 v[72:73], v[0:1]
	v_mov_b64_e32 v[82:83], v[0:1]
	v_mov_b64_e32 v[84:85], v[0:1]
	v_mov_b64_e32 v[86:87], v[0:1]
	v_mov_b64_e32 v[88:89], v[0:1]
	s_waitcnt vmcnt(0)
	v_mov_b64_e32 v[98:99], v[0:1]
	v_mov_b64_e32 v[100:101], v[0:1]
	v_mov_b64_e32 v[102:103], v[0:1]
	v_mov_b64_e32 v[104:105], v[0:1]
	v_mov_b64_e32 v[114:115], v[0:1]
	v_mov_b64_e32 v[116:117], v[0:1]
	v_mov_b64_e32 v[118:119], v[0:1]
	v_mov_b64_e32 v[120:121], v[0:1]
	v_mov_b64_e32 v[74:75], v[0:1]
	v_mov_b64_e32 v[76:77], v[0:1]
	v_mov_b64_e32 v[78:79], v[0:1]
	v_mov_b64_e32 v[80:81], v[0:1]
	v_mov_b64_e32 v[90:91], v[0:1]
	v_mov_b64_e32 v[92:93], v[0:1]
	v_mov_b64_e32 v[94:95], v[0:1]
	v_mov_b64_e32 v[96:97], v[0:1]
	v_mov_b64_e32 v[106:107], v[0:1]
	v_mov_b64_e32 v[108:109], v[0:1]
	v_mov_b64_e32 v[110:111], v[0:1]
	v_mov_b64_e32 v[112:113], v[0:1]
	v_mov_b64_e32 v[122:123], v[0:1]
	v_mov_b64_e32 v[124:125], v[0:1]
	v_mov_b64_e32 v[126:127], v[0:1]
	v_mov_b64_e32 v[128:129], v[0:1]
	s_mov_b32 s44, 0x3a800000

; template <class Epi>
; DI void gemm_phase(int wv, LAS unsigned char* lds, const Gemm g, const StaticOrder& S, const Epi& E) {
;     ...
;     const bool has_next = S.next(ui + 1, nxt);
;     const char* nA = has_next ? (const char*)g.A + (size_t)nxt.pm * tstep : cA; const char* nB = has_next ? (const char*)g.Bt + (size_t)nxt.pn * tstep : cB;
;     for (int t = 0; t < nt; t += 2) {
;       const bool last = (t == nt - 2);
;       const char* a1 = cA + (size_t)(t + 1) * kstep;
;       const char* a2 = last ? nA : cA + (size_t)(t + 2) * kstep; const char* b2 = last ? nB : cB + (size_t)(t + 2) * kstep;
;     ...
; #pragma unroll
;     for (int a = 0; a < 2; ++a)
; #pragma unroll
;       for (int b = 0; b < 2; ++b)
; #pragma unroll
;         for (int m = 0; m < 4; ++m)
; #pragma unroll
;           for (int n = 0; n < 2; ++n) acc[a][b][m][n] = (f32x4){0.f, 0.f, 0.f, 0.f};
.LBB0_889:
	s_add_u32 s30, s30, 0x80
	s_addc_u32 s31, s31, 0
	s_add_u32 s95, s34, 0x100
	v_mov_b32_e32 v0, 0
	s_addc_u32 vcc_lo, s35, 0
	s_mov_b32 s34, 0
	s_waitcnt lgkmcnt(0)
	v_mov_b32_e32 v1, v0
	v_mov_b64_e32 v[2:3], v[0:1]
	v_mov_b64_e32 v[4:5], v[0:1]
	v_mov_b64_e32 v[6:7], v[0:1]
	v_mov_b64_e32 v[16:17], v[0:1]
	v_mov_b64_e32 v[18:19], v[0:1]
	v_mov_b64_e32 v[20:21], v[0:1]
	v_mov_b64_e32 v[22:23], v[0:1]
	v_mov_b64_e32 v[34:35], v[0:1]
	v_mov_b64_e32 v[36:37], v[0:1]
	v_mov_b64_e32 v[38:39], v[0:1]
	v_mov_b64_e32 v[40:41], v[0:1]
	v_mov_b64_e32 v[50:51], v[0:1]
	v_mov_b64_e32 v[52:53], v[0:1]
	v_mov_b64_e32 v[54:55], v[0:1]
	v_mov_b64_e32 v[56:57], v[0:1]
	v_mov_b64_e32 v[8:9], v[0:1]
	v_mov_b64_e32 v[10:11], v[0:1]
	v_mov_b64_e32 v[12:13], v[0:1]
	v_mov_b64_e32 v[14:15], v[0:1]
	v_mov_b64_e32 v[24:25], v[0:1]
	v_mov_b64_e32 v[26:27], v[0:1]
	v_mov_b64_e32 v[28:29], v[0:1]
	v_mov_b64_e32 v[30:31], v[0:1]
	v_mov_b64_e32 v[42:43], v[0:1]
	v_mov_b64_e32 v[44:45], v[0:1]
	v_mov_b64_e32 v[46:47], v[0:1]
	v_mov_b64_e32 v[48:49], v[0:1]
	v_mov_b64_e32 v[62:63], v[0:1]
	v_mov_b64_e32 v[64:65], v[0:1]
	v_mov_b64_e32 v[70:71], v[0:1]
	v_mov_b64_e32 v[72:73], v[0:1]
	v_mov_b64_e32 v[74:75], v[0:1]
	v_mov_b64_e32 v[76:77], v[0:1]
	v_mov_b64_e32 v[78:79], v[0:1]
	v_mov_b64_e32 v[80:81], v[0:1]
	v_mov_b64_e32 v[90:91], v[0:1]
	v_mov_b64_e32 v[92:93], v[0:1]
	v_mov_b64_e32 v[94:95], v[0:1]
	v_mov_b64_e32 v[96:97], v[0:1]
	v_mov_b64_e32 v[106:107], v[0:1]
	v_mov_b64_e32 v[108:109], v[0:1]
	v_mov_b64_e32 v[110:111], v[0:1]
	v_mov_b64_e32 v[112:113], v[0:1]
	s_waitcnt vmcnt(0)
	v_mov_b64_e32 v[122:123], v[0:1]
	v_mov_b64_e32 v[124:125], v[0:1]
	v_mov_b64_e32 v[126:127], v[0:1]
	v_mov_b64_e32 v[128:129], v[0:1]
	v_mov_b64_e32 v[82:83], v[0:1]
	v_mov_b64_e32 v[84:85], v[0:1]
	v_mov_b64_e32 v[86:87], v[0:1]
	v_mov_b64_e32 v[88:89], v[0:1]
	v_mov_b64_e32 v[98:99], v[0:1]
	v_mov_b64_e32 v[100:101], v[0:1]
	v_mov_b64_e32 v[102:103], v[0:1]
	v_mov_b64_e32 v[104:105], v[0:1]
	v_mov_b64_e32 v[114:115], v[0:1]
	v_mov_b64_e32 v[116:117], v[0:1]
	v_mov_b64_e32 v[118:119], v[0:1]
	v_mov_b64_e32 v[120:121], v[0:1]
	v_mov_b64_e32 v[134:135], v[0:1]
	v_mov_b64_e32 v[136:137], v[0:1]
	v_mov_b64_e32 v[162:163], v[0:1]
	v_mov_b64_e32 v[164:165], v[0:1]
